# final output stores (down-projection epilogue) marked nt: the out tensor is never re-read; on v53 stack
# baseline (speedup 1.0000x reference)
;     __device__ __forceinline__ void operator()(const f32x4 (&acc)[2][2][4][2], const Unit& u, int wr, int wc, int fr, int fq) const {
;         const int col0 = u.pn * BM + wc * 32 + 8 * fq;
;         const int b = (u.pm * BM) / rows_per_batch;
;         const float* gp = gate + (size_t)b * gate_stride + col0;
;         f32x4 gv[2][2];
; #pragma unroll
;         for (int bj = 0; bj < 2; ++bj)
; #pragma unroll
;             for (int n = 0; n < 2; ++n) gv[bj][n] = *(const f32x4*)(gp + bj * HALF + 4 * n);
;         const size_t row0 = (size_t)(u.pm * BM + wr * 64 + fr) * ldc + col0;
;         u32x4 bs[2][2];
; #pragma unroll
;         for (int bj = 0; bj < 2; ++bj) bs[0][bj] = *(const u32x4*)(base + row0 + bj * HALF);
; #pragma unroll
;         for (int g = 0; g < 8; ++g) { const int ai = g >> 2, m = g & 3; const size_t off = row0 + (size_t)(ai * HALF + m * 16) * ldc;
;             if (g < 7) { const size_t offn = row0 + (size_t)(((g + 1) >> 2) * HALF + ((g + 1) & 3) * 16) * ldc;
; #pragma unroll
;                 for (int bj = 0; bj < 2; ++bj) bs[(g + 1) & 1][bj] = *(const u32x4*)(base + offn + bj * HALF); }
; #pragma unroll
;             for (int bj = 0; bj < 2; ++bj) { const u32x4 w = bs[g & 1][bj];
;                 const f32x4 x0 = {__builtin_bit_cast(float, w.x << 16), __builtin_bit_cast(float, w.x & 0xffff0000u), __builtin_bit_cast(float, w.y << 16), __builtin_bit_cast(float, w.y & 0xffff0000u)};
;                 const f32x4 x1 = {__builtin_bit_cast(float, w.z << 16), __builtin_bit_cast(float, w.z & 0xffff0000u), __builtin_bit_cast(float, w.w << 16), __builtin_bit_cast(float, w.w & 0xffff0000u)};
;                 *(f32x4*)(out + off + bj * HALF) = x0 + gv[bj][0] * acc[ai][bj][m][0];
;                 *(f32x4*)(out + off + bj * HALF + 4) = x1 + gv[bj][1] * acc[ai][bj][m][1]; }
;         }
;     }
.LBB0_2168:
	v_lshl_add_u32 v130, s53, 8, v164
	v_lshl_or_b32 v128, s54, 8, v166
	v_ashrrev_i32_e32 v131, 31, v130
	v_ashrrev_i32_e32 v129, 31, v128
	v_lshlrev_b64 v[130:131], 12, v[130:131]
	v_readlane_b32 s14, v252, 46
	v_lshl_add_u64 v[160:161], v[130:131], 0, v[128:129]
	v_readlane_b32 s15, v252, 47
	s_nop 1
	v_lshl_add_u64 v[162:163], v[160:161], 1, s[14:15]
	s_ashr_i32 s14, s53, 31
	s_lshr_b32 s14, s14, 28
	s_add_i32 s14, s53, s14
	s_ashr_i32 s14, s14, 4
	s_mul_hi_i32 s15, s14, 0x18000
	s_mul_i32 s14, s14, 0x18000
	global_load_dwordx4 v[170:173], v[162:163], off
	global_load_dwordx4 v[174:177], v[162:163], off offset:256
	s_add_u32 s14, s30, s14
	v_add_co_u32_e32 v182, vcc, s38, v162
	s_addc_u32 s15, s31, s15
	s_nop 0
	v_addc_co_u32_e32 v183, vcc, 0, v163, vcc
	v_lshl_add_u64 v[128:129], v[128:129], 2, s[14:15]
	global_load_dwordx4 v[178:181], v[182:183], off
	global_load_dwordx4 v[140:143], v[128:129], off
	global_load_dwordx4 v[136:139], v[128:129], off offset:16
	global_load_dwordx4 v[132:135], v[128:129], off offset:512
	s_nop 0
	global_load_dwordx4 v[128:131], v[128:129], off offset:528
	s_nop 0
	global_load_dwordx4 v[182:185], v[182:183], off offset:256
	v_lshl_add_u64 v[160:161], v[160:161], 2, s[80:81]
	v_add_co_u32_e32 v186, vcc, s39, v162
	s_waitcnt vmcnt(0)
	v_lshlrev_b32_e32 v192, 16, v170
	v_and_b32_e32 v193, 0xffff0000, v170
	v_lshlrev_b32_e32 v170, 16, v171
	v_and_b32_e32 v171, 0xffff0000, v171
	v_lshlrev_b32_e32 v194, 16, v172
	v_and_b32_e32 v195, 0xffff0000, v172
	v_lshlrev_b32_e32 v172, 16, v173
	v_and_b32_e32 v173, 0xffff0000, v173
	v_lshlrev_b32_e32 v196, 16, v174
	v_and_b32_e32 v197, 0xffff0000, v174
	v_lshlrev_b32_e32 v174, 16, v175
	v_and_b32_e32 v175, 0xffff0000, v175
	v_lshlrev_b32_e32 v198, 16, v176
	v_and_b32_e32 v199, 0xffff0000, v176
	v_lshlrev_b32_e32 v176, 16, v177
	v_and_b32_e32 v177, 0xffff0000, v177
	v_pk_fma_f32 v[126:127], v[126:127], v[142:143], v[170:171]
	v_pk_fma_f32 v[124:125], v[124:125], v[140:141], v[192:193]
	v_addc_co_u32_e32 v187, vcc, 0, v163, vcc
	v_pk_fma_f32 v[122:123], v[122:123], v[138:139], v[172:173]
	v_pk_fma_f32 v[120:121], v[120:121], v[136:137], v[194:195]
	v_pk_fma_f32 v[114:115], v[114:115], v[134:135], v[174:175]
	v_pk_fma_f32 v[112:113], v[112:113], v[132:133], v[196:197]
	v_pk_fma_f32 v[106:107], v[106:107], v[130:131], v[176:177]
	v_pk_fma_f32 v[104:105], v[104:105], v[128:129], v[198:199]
	global_store_dwordx4 v[160:161], v[124:127], off nt
	global_store_dwordx4 v[160:161], v[120:123], off offset:16 nt
	global_store_dwordx4 v[160:161], v[112:115], off offset:512 nt
	global_store_dwordx4 v[160:161], v[104:107], off offset:528 nt
	v_add_co_u32_e32 v188, vcc, s39, v160
	global_load_dwordx4 v[104:107], v[186:187], off
	global_load_dwordx4 v[112:115], v[186:187], off offset:256
	v_addc_co_u32_e32 v189, vcc, 0, v161, vcc
	v_lshlrev_b32_e32 v200, 16, v178
	v_and_b32_e32 v201, 0xffff0000, v178
	v_lshlrev_b32_e32 v178, 16, v179
	v_and_b32_e32 v179, 0xffff0000, v179
	v_add_co_u32_e32 v190, vcc, s40, v162
	v_lshlrev_b32_e32 v202, 16, v180
	v_and_b32_e32 v203, 0xffff0000, v180
	v_lshlrev_b32_e32 v120, 16, v181
	v_and_b32_e32 v121, 0xffff0000, v181
	v_lshlrev_b32_e32 v122, 16, v182
	v_and_b32_e32 v123, 0xffff0000, v182
	v_lshlrev_b32_e32 v124, 16, v183
	v_and_b32_e32 v125, 0xffff0000, v183
	v_lshlrev_b32_e32 v126, 16, v184
	v_and_b32_e32 v127, 0xffff0000, v184
	v_lshlrev_b32_e32 v170, 16, v185
	v_and_b32_e32 v171, 0xffff0000, v185
	v_pk_fma_f32 v[118:119], v[118:119], v[142:143], v[178:179]
	v_pk_fma_f32 v[116:117], v[116:117], v[140:141], v[200:201]
	v_addc_co_u32_e32 v191, vcc, 0, v163, vcc
	v_pk_fma_f32 v[110:111], v[110:111], v[138:139], v[120:121]
	v_pk_fma_f32 v[108:109], v[108:109], v[136:137], v[202:203]
	v_pk_fma_f32 v[102:103], v[102:103], v[134:135], v[124:125]
	v_pk_fma_f32 v[100:101], v[100:101], v[132:133], v[122:123]
	v_pk_fma_f32 v[98:99], v[98:99], v[130:131], v[170:171]
	v_pk_fma_f32 v[96:97], v[96:97], v[128:129], v[126:127]
	global_store_dwordx4 v[188:189], v[116:119], off nt
	global_store_dwordx4 v[188:189], v[108:111], off offset:16 nt
	global_store_dwordx4 v[188:189], v[100:103], off offset:512 nt
	global_store_dwordx4 v[188:189], v[96:99], off offset:528 nt
	global_load_dwordx4 v[96:99], v[190:191], off
	s_nop 0
	global_load_dwordx4 v[100:103], v[190:191], off offset:256
	v_add_co_u32_e32 v108, vcc, s41, v160
	s_waitcnt vmcnt(7)
	v_lshlrev_b32_e32 v120, 16, v104
	v_addc_co_u32_e32 v109, vcc, 0, v161, vcc
	v_add_co_u32_e32 v110, vcc, s42, v162
	v_and_b32_e32 v121, 0xffff0000, v104
	v_lshlrev_b32_e32 v104, 16, v105
	v_and_b32_e32 v105, 0xffff0000, v105
	v_addc_co_u32_e32 v111, vcc, 0, v163, vcc
	v_lshlrev_b32_e32 v122, 16, v106
	v_and_b32_e32 v123, 0xffff0000, v106
	v_lshlrev_b32_e32 v106, 16, v107
	v_and_b32_e32 v107, 0xffff0000, v107
	s_waitcnt vmcnt(6)
	v_lshlrev_b32_e32 v124, 16, v112
	v_and_b32_e32 v125, 0xffff0000, v112
	v_lshlrev_b32_e32 v112, 16, v113
	v_and_b32_e32 v113, 0xffff0000, v113
	v_lshlrev_b32_e32 v126, 16, v114
	v_and_b32_e32 v127, 0xffff0000, v114
	v_lshlrev_b32_e32 v114, 16, v115
	v_and_b32_e32 v115, 0xffff0000, v115
	v_pk_fma_f32 v[94:95], v[94:95], v[142:143], v[104:105]
	v_pk_fma_f32 v[92:93], v[92:93], v[140:141], v[120:121]
	v_add_co_u32_e32 v116, vcc, s43, v160
	v_pk_fma_f32 v[90:91], v[90:91], v[138:139], v[106:107]
	v_pk_fma_f32 v[88:89], v[88:89], v[136:137], v[122:123]
	v_pk_fma_f32 v[86:87], v[86:87], v[134:135], v[112:113]
	v_pk_fma_f32 v[84:85], v[84:85], v[132:133], v[124:125]
	v_pk_fma_f32 v[78:79], v[78:79], v[130:131], v[114:115]
	v_pk_fma_f32 v[76:77], v[76:77], v[128:129], v[126:127]
	global_store_dwordx4 v[108:109], v[92:95], off nt
	global_store_dwordx4 v[108:109], v[88:91], off offset:16 nt
	global_store_dwordx4 v[108:109], v[84:87], off offset:512 nt
	global_store_dwordx4 v[108:109], v[76:79], off offset:528 nt
	v_addc_co_u32_e32 v117, vcc, 0, v161, vcc
	s_waitcnt vmcnt(5)
;     __device__ __forceinline__ void operator()(const f32x4 (&acc)[2][2][4][2], const Unit& u, int wr, int wc, int fr, int fq) const {
;     ...
;         for (int g = 0; g < 8; ++g) { const int ai = g >> 2, m = g & 3; const size_t off = row0 + (size_t)(ai * HALF + m * 16) * ldc;
;             if (g < 7) { const size_t offn = row0 + (size_t)(((g + 1) >> 2) * HALF + ((g + 1) & 3) * 16) * ldc;
; #pragma unroll
;                 for (int bj = 0; bj < 2; ++bj) bs[(g + 1) & 1][bj] = *(const u32x4*)(base + offn + bj * HALF); }
; #pragma unroll
;             for (int bj = 0; bj < 2; ++bj) { const u32x4 w = bs[g & 1][bj];
;                 const f32x4 x0 = {__builtin_bit_cast(float, w.x << 16), __builtin_bit_cast(float, w.x & 0xffff0000u), __builtin_bit_cast(float, w.y << 16), __builtin_bit_cast(float, w.y & 0xffff0000u)};
;                 const f32x4 x1 = {__builtin_bit_cast(float, w.z << 16), __builtin_bit_cast(float, w.z & 0xffff0000u), __builtin_bit_cast(float, w.w << 16), __builtin_bit_cast(float, w.w & 0xffff0000u)};
;                 *(f32x4*)(out + off + bj * HALF) = x0 + gv[bj][0] * acc[ai][bj][m][0];
;                 *(f32x4*)(out + off + bj * HALF + 4) = x1 + gv[bj][1] * acc[ai][bj][m][1]; }
	v_lshlrev_b32_e32 v104, 16, v96
	v_and_b32_e32 v105, 0xffff0000, v96
	v_lshlrev_b32_e32 v96, 16, v97
	v_and_b32_e32 v97, 0xffff0000, v97
	global_load_dwordx4 v[76:79], v[110:111], off
	global_load_dwordx4 v[84:87], v[110:111], off offset:256
	v_add_co_u32_e32 v118, vcc, s44, v162
	v_lshlrev_b32_e32 v106, 16, v98
	v_and_b32_e32 v107, 0xffff0000, v98
	v_lshlrev_b32_e32 v88, 16, v99
	v_and_b32_e32 v89, 0xffff0000, v99
	s_waitcnt vmcnt(6)
	v_lshlrev_b32_e32 v90, 16, v100
	v_and_b32_e32 v91, 0xffff0000, v100
	v_lshlrev_b32_e32 v92, 16, v101
	v_and_b32_e32 v93, 0xffff0000, v101
	v_lshlrev_b32_e32 v94, 16, v102
	v_and_b32_e32 v95, 0xffff0000, v102
	v_lshlrev_b32_e32 v98, 16, v103
	v_and_b32_e32 v99, 0xffff0000, v103
	v_pk_fma_f32 v[82:83], v[82:83], v[142:143], v[96:97]
	v_pk_fma_f32 v[80:81], v[80:81], v[140:141], v[104:105]
	v_addc_co_u32_e32 v119, vcc, 0, v163, vcc
	v_pk_fma_f32 v[74:75], v[74:75], v[138:139], v[88:89]
	v_pk_fma_f32 v[72:73], v[72:73], v[136:137], v[106:107]
	v_pk_fma_f32 v[70:71], v[70:71], v[134:135], v[92:93]
	v_pk_fma_f32 v[68:69], v[68:69], v[132:133], v[90:91]
	v_pk_fma_f32 v[66:67], v[66:67], v[130:131], v[98:99]
	v_pk_fma_f32 v[64:65], v[64:65], v[128:129], v[94:95]
	global_store_dwordx4 v[116:117], v[80:83], off nt
	global_store_dwordx4 v[116:117], v[72:75], off offset:16 nt
	global_store_dwordx4 v[116:117], v[68:71], off offset:512 nt
	global_store_dwordx4 v[116:117], v[64:67], off offset:528 nt
	global_load_dwordx4 v[64:67], v[118:119], off
	s_nop 0
	global_load_dwordx4 v[68:71], v[118:119], off offset:256
	v_add_co_u32_e32 v72, vcc, s45, v160
	s_waitcnt vmcnt(7)
	v_lshlrev_b32_e32 v88, 16, v76
	v_addc_co_u32_e32 v73, vcc, 0, v161, vcc
	v_add_co_u32_e32 v74, vcc, s46, v162
	v_and_b32_e32 v89, 0xffff0000, v76
	s_nop 0
	v_addc_co_u32_e32 v75, vcc, 0, v163, vcc
	v_lshlrev_b32_e32 v76, 16, v77
	v_and_b32_e32 v77, 0xffff0000, v77
	v_add_co_u32_e32 v80, vcc, s47, v160
	v_lshlrev_b32_e32 v90, 16, v78
	v_and_b32_e32 v91, 0xffff0000, v78
	v_lshlrev_b32_e32 v78, 16, v79
	v_and_b32_e32 v79, 0xffff0000, v79
	s_waitcnt vmcnt(6)
	v_lshlrev_b32_e32 v92, 16, v84
	v_and_b32_e32 v93, 0xffff0000, v84
	v_lshlrev_b32_e32 v84, 16, v85
	v_and_b32_e32 v85, 0xffff0000, v85
	v_lshlrev_b32_e32 v94, 16, v86
	v_and_b32_e32 v95, 0xffff0000, v86
	v_lshlrev_b32_e32 v86, 16, v87
	v_and_b32_e32 v87, 0xffff0000, v87
	v_pk_fma_f32 v[62:63], v[62:63], v[142:143], v[76:77]
	v_pk_fma_f32 v[60:61], v[60:61], v[140:141], v[88:89]
	v_addc_co_u32_e32 v81, vcc, 0, v161, vcc
	v_pk_fma_f32 v[58:59], v[58:59], v[138:139], v[78:79]
	v_pk_fma_f32 v[56:57], v[56:57], v[136:137], v[90:91]
	v_pk_fma_f32 v[54:55], v[54:55], v[134:135], v[84:85]
	v_pk_fma_f32 v[52:53], v[52:53], v[132:133], v[92:93]
	v_pk_fma_f32 v[46:47], v[46:47], v[130:131], v[86:87]
	v_pk_fma_f32 v[44:45], v[44:45], v[128:129], v[94:95]
	s_waitcnt vmcnt(1)
	v_lshlrev_b32_e32 v76, 16, v64
	v_and_b32_e32 v77, 0xffff0000, v64
	v_lshlrev_b32_e32 v64, 16, v65
	v_and_b32_e32 v65, 0xffff0000, v65
	global_store_dwordx4 v[72:73], v[60:63], off nt
	global_store_dwordx4 v[72:73], v[56:59], off offset:16 nt
	global_store_dwordx4 v[72:73], v[52:55], off offset:512 nt
	global_store_dwordx4 v[72:73], v[44:47], off offset:528 nt
	v_add_co_u32_e32 v82, vcc, s48, v162
	v_lshlrev_b32_e32 v78, 16, v66
	v_and_b32_e32 v79, 0xffff0000, v66
	global_load_dwordx4 v[44:47], v[74:75], off
	global_load_dwordx4 v[52:55], v[74:75], off offset:256
	v_lshlrev_b32_e32 v56, 16, v67
	v_and_b32_e32 v57, 0xffff0000, v67
	s_waitcnt vmcnt(6)
; #define PG8_BAR __builtin_amdgcn_s_barrier()
;     __device__ __forceinline__ void operator()(const f32x4 (&acc)[2][2][4][2], const Unit& u, int wr, int wc, int fr, int fq) const {
;     ...
;         for (int g = 0; g < 8; ++g) { const int ai = g >> 2, m = g & 3; const size_t off = row0 + (size_t)(ai * HALF + m * 16) * ldc;
;             if (g < 7) { const size_t offn = row0 + (size_t)(((g + 1) >> 2) * HALF + ((g + 1) & 3) * 16) * ldc;
; #pragma unroll
;                 for (int bj = 0; bj < 2; ++bj) bs[(g + 1) & 1][bj] = *(const u32x4*)(base + offn + bj * HALF); }
; #pragma unroll
;             for (int bj = 0; bj < 2; ++bj) { const u32x4 w = bs[g & 1][bj];
;                 const f32x4 x0 = {__builtin_bit_cast(float, w.x << 16), __builtin_bit_cast(float, w.x & 0xffff0000u), __builtin_bit_cast(float, w.y << 16), __builtin_bit_cast(float, w.y & 0xffff0000u)};
;                 const f32x4 x1 = {__builtin_bit_cast(float, w.z << 16), __builtin_bit_cast(float, w.z & 0xffff0000u), __builtin_bit_cast(float, w.w << 16), __builtin_bit_cast(float, w.w & 0xffff0000u)};
;                 *(f32x4*)(out + off + bj * HALF) = x0 + gv[bj][0] * acc[ai][bj][m][0];
;                 *(f32x4*)(out + off + bj * HALF + 4) = x1 + gv[bj][1] * acc[ai][bj][m][1]; }
; template <class Epi, class Sched, bool ALIGN_EPI = false, bool SP2 = false>
; __device__ __forceinline__ void gemm_phase(PG8_LAS unsigned char* lds, const Gemm g, const Sched& S, const Epi& E) {
;     ...
;         if constexpr (!Epi::AFTER_DRAIN) { E(acc, cur, wr, wc, fr, fq); S.done(cur); }
;         if (!has_next) break;
; #pragma unroll
;         for (int a = 0; a < 2; ++a)
; #pragma unroll
;             for (int b = 0; b < 2; ++b)
; #pragma unroll
;                 for (int m = 0; m < 4; ++m)
; #pragma unroll
;                     for (int n = 0; n < 2; ++n) acc[a][b][m][n] = (f32x4){0.f, 0.f, 0.f, 0.f};
;         cur = nxt; cA = nA; cB = nB; ++ui;
;         if constexpr (ALIGN_EPI) { if (wr == 1) PG8_BAR; }
;     }
	v_lshlrev_b32_e32 v58, 16, v68
	v_and_b32_e32 v59, 0xffff0000, v68
	v_lshlrev_b32_e32 v60, 16, v69
	v_and_b32_e32 v61, 0xffff0000, v69
	v_lshlrev_b32_e32 v62, 16, v70
	v_and_b32_e32 v63, 0xffff0000, v70
	v_lshlrev_b32_e32 v66, 16, v71
	v_and_b32_e32 v67, 0xffff0000, v71
	v_pk_fma_f32 v[50:51], v[50:51], v[142:143], v[64:65]
	v_pk_fma_f32 v[48:49], v[48:49], v[140:141], v[76:77]
	v_addc_co_u32_e32 v83, vcc, 0, v163, vcc
	v_pk_fma_f32 v[42:43], v[42:43], v[138:139], v[56:57]
	v_pk_fma_f32 v[40:41], v[40:41], v[136:137], v[78:79]
	v_pk_fma_f32 v[38:39], v[38:39], v[134:135], v[60:61]
	v_pk_fma_f32 v[36:37], v[36:37], v[132:133], v[58:59]
	v_pk_fma_f32 v[34:35], v[34:35], v[130:131], v[66:67]
	v_pk_fma_f32 v[32:33], v[32:33], v[128:129], v[62:63]
	global_store_dwordx4 v[80:81], v[48:51], off nt
	global_store_dwordx4 v[80:81], v[40:43], off offset:16 nt
	global_store_dwordx4 v[80:81], v[36:39], off offset:512 nt
	global_store_dwordx4 v[80:81], v[32:35], off offset:528 nt
	global_load_dwordx4 v[32:35], v[82:83], off
	s_nop 0
	global_load_dwordx4 v[36:39], v[82:83], off offset:256
	v_add_co_u32_e32 v40, vcc, s49, v160
	s_waitcnt vmcnt(7)
	v_lshlrev_b32_e32 v48, 16, v44
	v_addc_co_u32_e32 v41, vcc, 0, v161, vcc
	v_add_co_u32_e32 v42, vcc, s50, v160
	v_and_b32_e32 v49, 0xffff0000, v44
	v_lshlrev_b32_e32 v44, 16, v45
	v_and_b32_e32 v45, 0xffff0000, v45
	s_waitcnt vmcnt(6)
	v_lshlrev_b32_e32 v58, 16, v54
	v_and_b32_e32 v59, 0xffff0000, v54
	v_lshlrev_b32_e32 v54, 16, v55
	v_and_b32_e32 v55, 0xffff0000, v55
	v_addc_co_u32_e32 v43, vcc, 0, v161, vcc
	v_lshlrev_b32_e32 v50, 16, v46
	v_and_b32_e32 v51, 0xffff0000, v46
	v_lshlrev_b32_e32 v46, 16, v47
	v_and_b32_e32 v47, 0xffff0000, v47
	v_lshlrev_b32_e32 v56, 16, v52
	v_and_b32_e32 v57, 0xffff0000, v52
	v_lshlrev_b32_e32 v52, 16, v53
	v_and_b32_e32 v53, 0xffff0000, v53
	v_pk_fma_f32 v[30:31], v[30:31], v[142:143], v[44:45]
	v_pk_fma_f32 v[28:29], v[28:29], v[140:141], v[48:49]
	v_pk_fma_f32 v[10:11], v[10:11], v[130:131], v[54:55]
	v_pk_fma_f32 v[8:9], v[8:9], v[128:129], v[58:59]
	s_waitcnt vmcnt(1)
	v_lshlrev_b32_e32 v44, 16, v32
	v_and_b32_e32 v45, 0xffff0000, v32
	v_lshlrev_b32_e32 v32, 16, v33
	v_and_b32_e32 v33, 0xffff0000, v33
	s_and_b64 vcc, exec, s[0:1]
	v_pk_fma_f32 v[26:27], v[26:27], v[138:139], v[46:47]
	v_pk_fma_f32 v[24:25], v[24:25], v[136:137], v[50:51]
	v_pk_fma_f32 v[18:19], v[18:19], v[134:135], v[52:53]
	v_pk_fma_f32 v[16:17], v[16:17], v[132:133], v[56:57]
	v_lshlrev_b32_e32 v46, 16, v34
	v_and_b32_e32 v47, 0xffff0000, v34
	v_lshlrev_b32_e32 v34, 16, v35
	v_and_b32_e32 v35, 0xffff0000, v35
	s_waitcnt vmcnt(0)
	v_lshlrev_b32_e32 v48, 16, v36
	v_and_b32_e32 v49, 0xffff0000, v36
	v_lshlrev_b32_e32 v36, 16, v37
	v_and_b32_e32 v37, 0xffff0000, v37
	v_lshlrev_b32_e32 v50, 16, v38
	v_and_b32_e32 v51, 0xffff0000, v38
	v_lshlrev_b32_e32 v38, 16, v39
	v_and_b32_e32 v39, 0xffff0000, v39
	global_store_dwordx4 v[40:41], v[28:31], off nt
	global_store_dwordx4 v[40:41], v[24:27], off offset:16 nt
	global_store_dwordx4 v[40:41], v[16:19], off offset:512 nt
	global_store_dwordx4 v[40:41], v[8:11], off offset:528 nt
	s_mov_b64 s[0:1], -1
	v_pk_fma_f32 v[14:15], v[14:15], v[138:139], v[34:35]
	v_pk_fma_f32 v[10:11], v[22:23], v[142:143], v[32:33]
	v_pk_fma_f32 v[8:9], v[20:21], v[140:141], v[44:45]
	v_pk_fma_f32 v[12:13], v[12:13], v[136:137], v[46:47]
	v_pk_fma_f32 v[6:7], v[6:7], v[134:135], v[36:37]
	v_pk_fma_f32 v[4:5], v[4:5], v[132:133], v[48:49]
	v_pk_fma_f32 v[2:3], v[2:3], v[130:131], v[38:39]
	v_pk_fma_f32 v[0:1], v[0:1], v[128:129], v[50:51]
	global_store_dwordx4 v[42:43], v[8:11], off nt
	global_store_dwordx4 v[42:43], v[12:15], off offset:16 nt
	global_store_dwordx4 v[42:43], v[4:7], off offset:512 nt
	global_store_dwordx4 v[42:43], v[0:3], off offset:528 nt
	s_cbranch_vccnz .LBB0_2153
	s_andn2_b64 vcc, exec, s[6:7]
	s_cbranch_vccnz .LBB0_2152
	s_barrier
	s_branch .LBB0_2152
